# baseline (speedup 1.0000x reference)
; __device__ __forceinline__ int otid() { int t = threadIdx.x; asm volatile("" : "+v"(t)); return t; }
; __device__ void transpose_tile(const float* __restrict__ src, u16* __restrict__ dst, int K, int N, int k0, int n0,
;                                const float* __restrict__ kscale) {
;     ...
;   const int tid = otid();
;   {
;     const int kk = tid >> 4, nn4 = (tid & 15) * 4;
;     #pragma unroll
;     for (int h = 0; h < 2; ++h) {
;       const int k = kk + h * 32;
;       float4 v = *reinterpret_cast<const float4*>(src + (size_t)(k0 + k) * N + n0 + nn4);
; __device__ void phase0(const Params& p) {
;     ...
;   for (int t = b; t < T_ALL; t += G) {
;     int u = t;
;     if (u < T_WIN) { transpose_tile(p.w_in, (u16*)(ws + OFF_WIN), 2048, NIN, (u % 32) * 64, (u / 32) * 64, p.g_pre); continue; }
;     u -= T_WIN;
;     if (u < T_WA) { transpose_tile(p.w_a, (u16*)(ws + OFF_WA), 2048, 2048, (u % 32) * 64, (u / 32) * 64, nullptr); continue; }
;     u -= T_WA;
;     if (u < T_WB) { transpose_tile(p.w_b, (u16*)(ws + OFF_WB), 1024, 2048, (u % 16) * 64, (u / 16) * 64, nullptr); continue; }
;     u -= T_WB;
;     if (u < T_WOUT) { transpose_tile(p.w_out, (u16*)(ws + OFF_WOUT), 2048, 2048, (u % 32) * 64, (u / 32) * 64, nullptr); continue; }
;     u -= T_WOUT;
;     if (u < T_WPG) { transpose_tile(p.w_pg, (u16*)(ws + OFF_WPG), 2048, 2048, (u % 32) * 64, (u / 32) * 64, nullptr); continue; }
.LBB0_20:
	s_or_b64 exec, exec, s[4:5]
	v_mov_b32_e32 v1, 0x20000
	s_load_dwordx16 s[36:51], s[0:1], 0x0
	s_load_dwordx16 s[52:67], s[0:1], 0x40
	s_waitcnt lgkmcnt(0)
	s_barrier
	ds_read_b96 v[2:4], v1
	v_mov_b32_e32 v1, v194
	s_cmpk_gt_i32 s2, 0x237f
	s_waitcnt lgkmcnt(0)
	v_readfirstlane_b32 s0, v2
	v_readfirstlane_b32 s87, v3
	v_readfirstlane_b32 s86, v4
	v_writelane_b32 v254, s0, 0
	s_cbranch_scc1 .LBB0_51
	s_add_u32 s3, s30, 0x4600000
	s_addc_u32 s24, s31, 0
	s_add_u32 s4, s30, 0x4500000
	s_addc_u32 s5, s31, 0
	s_add_u32 s6, s30, 0x3d00000
	s_addc_u32 s7, s31, 0
	s_add_u32 s8, s30, 0x3500000
	s_addc_u32 s9, s31, 0
	s_add_u32 s10, s30, 0x3100000
	s_addc_u32 s11, s31, 0
	s_add_u32 s12, s30, 0x2900000
	s_addc_u32 s13, s31, 0
	s_add_u32 s14, s30, 0x100000
	s_addc_u32 s15, s31, 0
	s_cmp_lg_u64 s[44:45], 0
	s_cselect_b64 s[18:19], -1, 0
	s_lshl_b32 s25, s2, 6
	s_lshl_b32 s34, s33, 6
	s_lshl_b32 s35, s2, 5
	s_lshl_b32 s76, s33, 5
	s_lshl_b32 s77, s2, 4
	s_lshl_b32 s78, s33, 4
	s_lshl_b32 s79, s2, 1
	s_lshl_b32 s80, s33, 1
	s_lshl_b32 s81, s2, 2
	s_lshl_b32 s82, s33, 2
	s_mov_b32 s21, 0
	v_mov_b32_e32 v11, 0
	s_movk_i32 s83, 0x104
	s_mov_b32 s84, 0xa000
	v_cndmask_b32_e64 v13, 0, 1, s[18:19]
	s_mov_b32 s85, s2
	v_lshrrev_b32_e32 v119, 4, v194
	v_and_b32_e32 v118, 15, v194
	v_lshlrev_b32_e32 v118, 4, v118
	v_mul_u32_u24_e32 v100, 0xa000, v119
	v_add_u32_e32 v100, v100, v118
	v_lshlrev_b32_e32 v101, 2, v119
	v_lshl_add_u32 v184, v119, 13, v118
	v_mul_u32_u24_e32 v102, 0x104, v119
	v_add_u32_e32 v102, v102, v118
	v_add_u32_e32 v103, 0x4100, v102
	v_add_u32_e32 v104, 0x8200, v102
	v_add_u32_e32 v105, 0xc300, v102
	v_add_u32_e32 v106, 0x2080, v102
	v_add_u32_e32 v107, 0x2080, v103
	v_add_u32_e32 v108, 0x2080, v104
	v_add_u32_e32 v109, 0x2080, v105
	v_lshrrev_b32_e32 v119, 3, v194
	v_and_b32_e32 v118, 7, v194
	v_lshlrev_b32_e32 v118, 3, v118
	v_mul_u32_u24_e32 v110, 0x104, v118
	v_lshl_add_u32 v110, v119, 2, v110
	v_add_u32_e32 v111, 0x4100, v110
	v_add_u32_e32 v112, 0x8200, v110
	v_add_u32_e32 v113, 0xc300, v110
	v_add_u32_e32 v114, 0x400, v110
	v_add_u32_e32 v115, 0x400, v111
	v_add_u32_e32 v116, 0x400, v112
	v_add_u32_e32 v117, 0x400, v113
	v_lshlrev_b32_e32 v118, 1, v118
	v_lshl_add_u32 v118, v119, 12, v118

; __device__ __forceinline__ int otid() { int t = threadIdx.x; asm volatile("" : "+v"(t)); return t; }
; __device__ void transpose_tile(const float* __restrict__ src, u16* __restrict__ dst, int K, int N, int k0, int n0,
;                                const float* __restrict__ kscale) {
;   float* tile = reinterpret_cast<float*>(g_smem);
;   const int tid = otid();
;   {
;     const int kk = tid >> 4, nn4 = (tid & 15) * 4;
;     #pragma unroll
;     for (int h = 0; h < 2; ++h) {
;       const int k = kk + h * 32;
;       float4 v = *reinterpret_cast<const float4*>(src + (size_t)(k0 + k) * N + n0 + nn4);
;       float sc = kscale ? kscale[k0 + k] : 1.f;
;       tile[k * 65 + nn4 + 0] = v.x * sc; tile[k * 65 + nn4 + 1] = v.y * sc;
;       tile[k * 65 + nn4 + 2] = v.z * sc; tile[k * 65 + nn4 + 3] = v.w * sc;
;     }
;   }
;   __syncthreads();
;   {
;     const int nn = tid >> 3, kk8 = (tid & 7) * 8;
;     v4u o;
;     o.x = pk2(tile[(kk8 + 0) * 65 + nn], tile[(kk8 + 1) * 65 + nn]);
;     o.y = pk2(tile[(kk8 + 2) * 65 + nn], tile[(kk8 + 3) * 65 + nn]);
;     o.z = pk2(tile[(kk8 + 4) * 65 + nn], tile[(kk8 + 5) * 65 + nn]);
;     o.w = pk2(tile[(kk8 + 6) * 65 + nn], tile[(kk8 + 7) * 65 + nn]);
;     *reinterpret_cast<v4u*>(dst + (size_t)(n0 + nn) * K + k0 + kk8) = o;
;   }
;   __syncthreads();
; }
; __device__ void phase0(const Params& p) {
;     ...
;   for (int t = b; t < T_ALL; t += G) {
;     int u = t;
;     if (u < T_WIN) { transpose_tile(p.w_in, (u16*)(ws + OFF_WIN), 2048, NIN, (u % 32) * 64, (u / 32) * 64, p.g_pre); continue; }
;     u -= T_WIN;
;     if (u < T_WA) { transpose_tile(p.w_a, (u16*)(ws + OFF_WA), 2048, 2048, (u % 32) * 64, (u / 32) * 64, nullptr); continue; }
;     u -= T_WA;
;     if (u < T_WB) { transpose_tile(p.w_b, (u16*)(ws + OFF_WB), 1024, 2048, (u % 16) * 64, (u / 16) * 64, nullptr); continue; }
;     u -= T_WB;
;     if (u < T_WOUT) { transpose_tile(p.w_out, (u16*)(ws + OFF_WOUT), 2048, 2048, (u % 32) * 64, (u / 32) * 64, nullptr); continue; }
;     u -= T_WOUT;
;     if (u < T_WPG) { transpose_tile(p.w_pg, (u16*)(ws + OFF_WPG), 2048, 2048, (u % 32) * 64, (u / 32) * 64, nullptr); continue; }
.Lp0_latch_cmp:
	s_cmpk_gt_i32 s85, 0x237f
	s_cbranch_scc1 .LBB0_51
.LBB0_24:
	s_mul_i32 s92, s33, 3
	s_add_i32 s92, s92, s85
	s_cmpk_lt_u32 s85, 0x1400
	s_cbranch_scc1 .Lp0_nobatch
	s_cmpk_lt_u32 s92, 0x1800
	s_cbranch_scc1 .Lp0_wa
	s_cmpk_lt_u32 s85, 0x1a00
	s_cbranch_scc1 .Lp0_nobatch
	s_cmpk_lt_u32 s92, 0x1e00
	s_cbranch_scc1 .Lp0_wout
	s_cmpk_lt_u32 s85, 0x1e00
	s_cbranch_scc1 .Lp0_nobatch
	s_cmpk_lt_u32 s92, 0x2200
	s_cbranch_scc1 .Lp0_wpg
	s_branch .Lp0_nobatch
.Lp0_wa:
	s_mov_b64 s[96:97], s[62:63]
	s_mov_b64 s[98:99], s[12:13]
	s_movk_i32 s93, 0x1400
	s_branch .Lp0_plain
.Lp0_wout:
	s_mov_b64 s[96:97], s[66:67]
	s_mov_b64 s[98:99], s[8:9]
	s_movk_i32 s93, 0x1a00
	s_branch .Lp0_plain
.Lp0_wpg:
	s_mov_b64 s[96:97], s[72:73]
	s_mov_b64 s[98:99], s[6:7]
	s_movk_i32 s93, 0x1e00
.Lp0_plain:
	s_sub_i32 s92, s85, s93
	s_and_b32 s94, s92, 31
	s_lshl_b32 s94, s94, 6
	s_lshr_b32 s95, s92, 5
	s_lshl_b32 s95, s95, 6
	s_lshl_b32 s100, s94, 13
	s_lshl_b32 s101, s95, 2
	s_add_i32 s100, s100, s101
	v_add_u32_e32 v168, s100, v184
	v_add_u32_e32 v172, 0x40000, v168
	global_load_dwordx4 v[120:123], v168, s[96:97]
	global_load_dwordx4 v[124:127], v172, s[96:97]
	s_lshl_b32 s100, s95, 12
	s_lshl_b32 s101, s94, 1
	s_add_i32 s100, s100, s101
	v_add_u32_e32 v180, s100, v118
	s_add_i32 s92, s92, s33
	s_and_b32 s94, s92, 31
	s_lshl_b32 s94, s94, 6
	s_lshr_b32 s95, s92, 5
	s_lshl_b32 s95, s95, 6
	s_lshl_b32 s100, s94, 13
	s_lshl_b32 s101, s95, 2
	s_add_i32 s100, s100, s101
	v_add_u32_e32 v169, s100, v184
	v_add_u32_e32 v173, 0x40000, v169
	global_load_dwordx4 v[128:131], v169, s[96:97]
	global_load_dwordx4 v[132:135], v173, s[96:97]
	s_lshl_b32 s100, s95, 12
	s_lshl_b32 s101, s94, 1
	s_add_i32 s100, s100, s101
	v_add_u32_e32 v181, s100, v118
	s_add_i32 s92, s92, s33
	s_and_b32 s94, s92, 31
	s_lshl_b32 s94, s94, 6
	s_lshr_b32 s95, s92, 5
	s_lshl_b32 s95, s95, 6
	s_lshl_b32 s100, s94, 13
	s_lshl_b32 s101, s95, 2
	s_add_i32 s100, s100, s101
	v_add_u32_e32 v170, s100, v184
	v_add_u32_e32 v174, 0x40000, v170
	global_load_dwordx4 v[136:139], v170, s[96:97]
	global_load_dwordx4 v[140:143], v174, s[96:97]
	s_lshl_b32 s100, s95, 12
	s_lshl_b32 s101, s94, 1
	s_add_i32 s100, s100, s101
	v_add_u32_e32 v182, s100, v118
	s_add_i32 s92, s92, s33
	s_and_b32 s94, s92, 31
	s_lshl_b32 s94, s94, 6
	s_lshr_b32 s95, s92, 5
	s_lshl_b32 s95, s95, 6
	s_lshl_b32 s100, s94, 13
	s_lshl_b32 s101, s95, 2
	s_add_i32 s100, s100, s101
	v_add_u32_e32 v171, s100, v184
	v_add_u32_e32 v175, 0x40000, v171
	global_load_dwordx4 v[144:147], v171, s[96:97]
	global_load_dwordx4 v[148:151], v175, s[96:97]
	s_lshl_b32 s100, s95, 12
	s_lshl_b32 s101, s94, 1
	s_add_i32 s100, s100, s101
	v_add_u32_e32 v183, s100, v118
	s_waitcnt vmcnt(6)
	ds_write2_b32 v102, v120, v121 offset1:1
	ds_write2_b32 v102, v122, v123 offset0:2 offset1:3
	ds_write2_b32 v106, v124, v125 offset1:1
	ds_write2_b32 v106, v126, v127 offset0:2 offset1:3
	s_waitcnt vmcnt(4)
	ds_write2_b32 v103, v128, v129 offset1:1
	ds_write2_b32 v103, v130, v131 offset0:2 offset1:3
	ds_write2_b32 v107, v132, v133 offset1:1
	ds_write2_b32 v107, v134, v135 offset0:2 offset1:3
	s_waitcnt vmcnt(2)
	ds_write2_b32 v104, v136, v137 offset1:1
	ds_write2_b32 v104, v138, v139 offset0:2 offset1:3
	ds_write2_b32 v108, v140, v141 offset1:1
	ds_write2_b32 v108, v142, v143 offset0:2 offset1:3
	s_waitcnt vmcnt(0)
	ds_write2_b32 v105, v144, v145 offset1:1
	ds_write2_b32 v105, v146, v147 offset0:2 offset1:3
	ds_write2_b32 v109, v148, v149 offset1:1
	ds_write2_b32 v109, v150, v151 offset0:2 offset1:3
	s_waitcnt lgkmcnt(0)
	s_barrier
	ds_read2_b32 v[120:121], v110 offset1:65
	ds_read2_b32 v[122:123], v110 offset0:130 offset1:195
	ds_read2_b32 v[124:125], v114 offset0:4 offset1:69
	ds_read2_b32 v[126:127], v114 offset0:134 offset1:199
	ds_read2_b32 v[128:129], v111 offset1:65
	ds_read2_b32 v[130:131], v111 offset0:130 offset1:195
	ds_read2_b32 v[132:133], v115 offset0:4 offset1:69
	ds_read2_b32 v[134:135], v115 offset0:134 offset1:199
	ds_read2_b32 v[136:137], v112 offset1:65
	ds_read2_b32 v[138:139], v112 offset0:130 offset1:195
	ds_read2_b32 v[140:141], v116 offset0:4 offset1:69
	ds_read2_b32 v[142:143], v116 offset0:134 offset1:199
	ds_read2_b32 v[144:145], v113 offset1:65
	ds_read2_b32 v[146:147], v113 offset0:130 offset1:195
	ds_read2_b32 v[148:149], v117 offset0:4 offset1:69
	ds_read2_b32 v[150:151], v117 offset0:134 offset1:199
	s_waitcnt lgkmcnt(12)
	v_cvt_pk_bf16_f32 v120, v120, v121
	v_cvt_pk_bf16_f32 v121, v122, v123
	v_cvt_pk_bf16_f32 v122, v124, v125
	v_cvt_pk_bf16_f32 v123, v126, v127
	global_store_dwordx4 v180, v[120:123], s[98:99]
	s_waitcnt lgkmcnt(8)
	v_cvt_pk_bf16_f32 v128, v128, v129
	v_cvt_pk_bf16_f32 v129, v130, v131
	v_cvt_pk_bf16_f32 v130, v132, v133
	v_cvt_pk_bf16_f32 v131, v134, v135
	global_store_dwordx4 v181, v[128:131], s[98:99]
	s_waitcnt lgkmcnt(4)
	v_cvt_pk_bf16_f32 v136, v136, v137
	v_cvt_pk_bf16_f32 v137, v138, v139
	v_cvt_pk_bf16_f32 v138, v140, v141
	v_cvt_pk_bf16_f32 v139, v142, v143
	global_store_dwordx4 v182, v[136:139], s[98:99]
	s_waitcnt lgkmcnt(0)
	v_cvt_pk_bf16_f32 v144, v144, v145
	v_cvt_pk_bf16_f32 v145, v146, v147
	v_cvt_pk_bf16_f32 v146, v148, v149
	v_cvt_pk_bf16_f32 v147, v150, v151
	global_store_dwordx4 v183, v[144:147], s[98:99]
	s_barrier
	s_lshl_b32 s92, s33, 2
	s_add_i32 s85, s85, s92
	s_lshl_b32 s25, s85, 6
	s_lshl_b32 s35, s85, 5
	s_lshl_b32 s77, s85, 4
	s_lshl_b32 s79, s85, 1
	s_lshl_b32 s81, s85, 2
	s_branch .Lp0_latch_cmp
